# GEMM main loops: s_setprio moved to the far side of the phase barriers (nothing but the barrier between a phase's last MFMA and its rendezvous, MFMA issue right after release)
# speedup vs baseline: 1.0042x; 1.0042x over previous
.LBB0_174:
	s_add_u32 s22, s4, 0xfffc0080
	s_addc_u32 s23, s5, -1
	s_add_i32 s54, 0, 0x10000
	s_cmp_eq_u32 s53, 12
	s_cselect_b32 s25, s3, s23
	s_cselect_b32 s24, s17, s22
	v_add_u32_e32 v0, s54, v173
	s_cselect_b32 s23, s15, s52
	s_cselect_b32 s22, s50, s51
	s_add_i32 s56, 0, 0x14000
	ds_read_b128 v[130:133], v0
	ds_read_b128 v[134:137], v0 offset:1024
	ds_read_b128 v[138:141], v0 offset:2048
	ds_read_b128 v[142:145], v0 offset:3072
	v_add_u32_e32 v0, s56, v173
	ds_read_b128 v[146:149], v0
	ds_read_b128 v[174:177], v0 offset:1024
	ds_read_b128 v[180:183], v0 offset:2048
	ds_read_b128 v[184:187], v0 offset:3072
	v_lshl_add_u64 v[170:171], s[4:5], 0, v[166:167]
	s_add_i32 m0, s31, 0xc000
	ds_read_b128 v[188:191], v179
	ds_read_b128 v[192:195], v179 offset:1024
	ds_read_b128 v[196:199], v179 offset:2048
	ds_read_b128 v[200:203], v179 offset:3072
	ds_read_b128 v[204:207], v179 offset:4096
	ds_read_b128 v[208:211], v179 offset:5120
	ds_read_b128 v[212:215], v179 offset:6144
	ds_read_b128 v[242:245], v179 offset:7168
	global_load_lds_dwordx4 v[170:171], off
	v_lshl_add_u64 v[170:171], s[4:5], 0, v[168:169]
	s_add_i32 m0, s31, 0xe000
	s_nop 0
	global_load_lds_dwordx4 v[170:171], off
	s_waitcnt vmcnt(8)
	s_waitcnt lgkmcnt(0)
	s_setprio 1
	s_barrier
	s_waitcnt lgkmcnt(0)
	v_mfma_f32_16x16x32_bf16 v[78:81], v[130:133], v[188:191], v[78:81]
	v_mfma_f32_16x16x32_bf16 v[74:77], v[138:141], v[188:191], v[74:77]
	v_mfma_f32_16x16x32_bf16 v[70:73], v[130:133], v[196:199], v[70:73]
	v_mfma_f32_16x16x32_bf16 v[62:65], v[138:141], v[196:199], v[62:65]
	v_mfma_f32_16x16x32_bf16 v[54:57], v[130:133], v[204:207], v[54:57]
	v_mfma_f32_16x16x32_bf16 v[50:53], v[138:141], v[204:207], v[50:53]
	v_mfma_f32_16x16x32_bf16 v[42:45], v[130:133], v[212:215], v[42:45]
	v_mfma_f32_16x16x32_bf16 v[34:37], v[138:141], v[212:215], v[34:37]
	v_mfma_f32_16x16x32_bf16 v[78:81], v[134:137], v[192:195], v[78:81]
	v_mfma_f32_16x16x32_bf16 v[74:77], v[142:145], v[192:195], v[74:77]
	v_mfma_f32_16x16x32_bf16 v[70:73], v[134:137], v[200:203], v[70:73]
	v_mfma_f32_16x16x32_bf16 v[62:65], v[142:145], v[200:203], v[62:65]
	v_mfma_f32_16x16x32_bf16 v[54:57], v[134:137], v[208:211], v[54:57]
	v_mfma_f32_16x16x32_bf16 v[50:53], v[142:145], v[208:211], v[50:53]
	v_mfma_f32_16x16x32_bf16 v[42:45], v[134:137], v[242:245], v[42:45]
	v_mfma_f32_16x16x32_bf16 v[34:37], v[142:145], v[242:245], v[34:37]
	s_setprio 0
	s_setprio 1
	v_mfma_f32_16x16x32_bf16 v[126:129], v[146:149], v[188:191], v[126:129]
	v_mfma_f32_16x16x32_bf16 v[122:125], v[180:183], v[188:191], v[122:125]
	v_mfma_f32_16x16x32_bf16 v[118:121], v[146:149], v[196:199], v[118:121]
	v_mfma_f32_16x16x32_bf16 v[114:117], v[180:183], v[196:199], v[114:117]
	v_mfma_f32_16x16x32_bf16 v[110:113], v[146:149], v[204:207], v[110:113]
	v_mfma_f32_16x16x32_bf16 v[106:109], v[180:183], v[204:207], v[106:109]
	v_mfma_f32_16x16x32_bf16 v[102:105], v[146:149], v[212:215], v[102:105]
	v_mfma_f32_16x16x32_bf16 v[98:101], v[180:183], v[212:215], v[98:101]
	v_mfma_f32_16x16x32_bf16 v[126:129], v[174:177], v[192:195], v[126:129]
	v_mfma_f32_16x16x32_bf16 v[122:125], v[184:187], v[192:195], v[122:125]
	v_mfma_f32_16x16x32_bf16 v[118:121], v[174:177], v[200:203], v[118:121]
	v_mfma_f32_16x16x32_bf16 v[114:117], v[184:187], v[200:203], v[114:117]
	v_mfma_f32_16x16x32_bf16 v[110:113], v[174:177], v[208:211], v[110:113]
	v_mfma_f32_16x16x32_bf16 v[106:109], v[184:187], v[208:211], v[106:109]
	v_mfma_f32_16x16x32_bf16 v[102:105], v[174:177], v[242:245], v[102:105]
	v_mfma_f32_16x16x32_bf16 v[98:101], v[184:187], v[242:245], v[98:101]
	s_barrier
	s_setprio 0
	s_add_i32 s54, s54, s28
	v_lshl_add_u64 v[170:171], s[22:23], 0, v[154:155]
	s_mov_b32 m0, s54
	ds_read_b128 v[188:191], v179 offset:16384
	ds_read_b128 v[192:195], v179 offset:17408
	ds_read_b128 v[196:199], v179 offset:18432
	ds_read_b128 v[200:203], v179 offset:19456
	ds_read_b128 v[204:207], v179 offset:20480
	ds_read_b128 v[208:211], v179 offset:21504
	ds_read_b128 v[212:215], v179 offset:22528
	ds_read_b128 v[242:245], v179 offset:23552
	global_load_lds_dwordx4 v[170:171], off
	s_add_i32 m0, s54, 0x2000
	s_add_u32 s54, s22, 0x40000
	v_lshl_add_u64 v[226:227], s[22:23], 0, v[150:151]
	s_addc_u32 s55, s23, 0
	s_add_i32 s56, s56, s28
	global_load_lds_dwordx4 v[226:227], off
	v_lshl_add_u64 v[246:247], s[54:55], 0, v[154:155]
	s_mov_b32 m0, s56
	v_lshl_add_u64 v[228:229], s[24:25], 0, v[152:153]
	global_load_lds_dwordx4 v[246:247], off
	v_lshl_add_u64 v[246:247], s[54:55], 0, v[150:151]
	s_add_i32 m0, s56, 0x2000
	s_nop 0
	global_load_lds_dwordx4 v[246:247], off
	v_lshl_add_u64 v[246:247], s[24:25], 0, v[156:157]
	s_mov_b32 m0, s31
	s_nop 0
	global_load_lds_dwordx4 v[246:247], off
	s_mov_b32 m0, s34
	s_nop 0
	global_load_lds_dwordx4 v[228:229], off
	s_waitcnt vmcnt(8)
	s_waitcnt lgkmcnt(0)
	s_setprio 1
	s_barrier
	s_waitcnt lgkmcnt(0)
	v_mfma_f32_16x16x32_bf16 v[30:33], v[130:133], v[188:191], v[30:33]
	v_mfma_f32_16x16x32_bf16 v[26:29], v[138:141], v[188:191], v[26:29]
	v_mfma_f32_16x16x32_bf16 v[22:25], v[130:133], v[196:199], v[22:25]
	v_mfma_f32_16x16x32_bf16 v[18:21], v[138:141], v[196:199], v[18:21]
	v_mfma_f32_16x16x32_bf16 v[14:17], v[130:133], v[204:207], v[14:17]
	v_mfma_f32_16x16x32_bf16 v[10:13], v[138:141], v[204:207], v[10:13]
	v_mfma_f32_16x16x32_bf16 v[6:9], v[130:133], v[212:215], v[6:9]
	v_mfma_f32_16x16x32_bf16 v[2:5], v[138:141], v[212:215], v[2:5]
	v_mfma_f32_16x16x32_bf16 v[30:33], v[134:137], v[192:195], v[30:33]
	v_mfma_f32_16x16x32_bf16 v[26:29], v[142:145], v[192:195], v[26:29]
	v_mfma_f32_16x16x32_bf16 v[22:25], v[134:137], v[200:203], v[22:25]
	v_mfma_f32_16x16x32_bf16 v[18:21], v[142:145], v[200:203], v[18:21]
	v_mfma_f32_16x16x32_bf16 v[14:17], v[134:137], v[208:211], v[14:17]
	v_mfma_f32_16x16x32_bf16 v[10:13], v[142:145], v[208:211], v[10:13]
	v_mfma_f32_16x16x32_bf16 v[6:9], v[134:137], v[242:245], v[6:9]
	v_mfma_f32_16x16x32_bf16 v[2:5], v[142:145], v[242:245], v[2:5]
	s_setprio 0
	s_setprio 1
	v_mfma_f32_16x16x32_bf16 v[94:97], v[146:149], v[188:191], v[94:97]
	v_mfma_f32_16x16x32_bf16 v[90:93], v[180:183], v[188:191], v[90:93]
	v_mfma_f32_16x16x32_bf16 v[86:89], v[146:149], v[196:199], v[86:89]
	v_mfma_f32_16x16x32_bf16 v[82:85], v[180:183], v[196:199], v[82:85]
	v_mfma_f32_16x16x32_bf16 v[66:69], v[146:149], v[204:207], v[66:69]
	v_mfma_f32_16x16x32_bf16 v[58:61], v[180:183], v[204:207], v[58:61]
	v_mfma_f32_16x16x32_bf16 v[46:49], v[146:149], v[212:215], v[46:49]
	v_mfma_f32_16x16x32_bf16 v[38:41], v[180:183], v[212:215], v[38:41]
	v_mfma_f32_16x16x32_bf16 v[94:97], v[174:177], v[192:195], v[94:97]
	v_mfma_f32_16x16x32_bf16 v[90:93], v[184:187], v[192:195], v[90:93]
	v_mfma_f32_16x16x32_bf16 v[86:89], v[174:177], v[200:203], v[86:89]
	v_mfma_f32_16x16x32_bf16 v[82:85], v[184:187], v[200:203], v[82:85]
	v_mfma_f32_16x16x32_bf16 v[66:69], v[174:177], v[208:211], v[66:69]
	v_mfma_f32_16x16x32_bf16 v[58:61], v[184:187], v[208:211], v[58:61]
	v_mfma_f32_16x16x32_bf16 v[46:49], v[174:177], v[242:245], v[46:49]
	v_mfma_f32_16x16x32_bf16 v[38:41], v[184:187], v[242:245], v[38:41]
	s_barrier
	s_setprio 0
	s_add_i32 s54, 0, 0x18000
	v_add_u32_e32 v0, s54, v173
	s_add_i32 s55, 0, 0x1c000
	ds_read_b128 v[130:133], v0
	ds_read_b128 v[134:137], v0 offset:1024
	ds_read_b128 v[138:141], v0 offset:2048
	ds_read_b128 v[142:145], v0 offset:3072
	v_add_u32_e32 v0, s55, v173
	ds_read_b128 v[146:149], v0
	ds_read_b128 v[174:177], v0 offset:1024
	ds_read_b128 v[180:183], v0 offset:2048
	ds_read_b128 v[184:187], v0 offset:3072
	s_add_u32 s24, s24, 0x40000
	s_addc_u32 s25, s25, 0
	s_mov_b32 m0, s35
	v_lshl_add_u64 v[230:231], s[24:25], 0, v[156:157]
	ds_read_b128 v[188:191], v179 offset:32768
	ds_read_b128 v[192:195], v179 offset:33792
	ds_read_b128 v[196:199], v179 offset:34816
	ds_read_b128 v[200:203], v179 offset:35840
	ds_read_b128 v[204:207], v179 offset:36864
	ds_read_b128 v[208:211], v179 offset:37888
	ds_read_b128 v[212:215], v179 offset:38912
	ds_read_b128 v[242:245], v179 offset:39936
	global_load_lds_dwordx4 v[230:231], off
	v_lshl_add_u64 v[230:231], s[24:25], 0, v[152:153]
	s_mov_b32 m0, s36
	s_nop 0
	global_load_lds_dwordx4 v[230:231], off
	s_waitcnt vmcnt(8)
	s_waitcnt lgkmcnt(0)
	s_setprio 1
	s_barrier
	s_waitcnt lgkmcnt(0)
	v_mfma_f32_16x16x32_bf16 v[78:81], v[130:133], v[188:191], v[78:81]
	v_mfma_f32_16x16x32_bf16 v[74:77], v[138:141], v[188:191], v[74:77]
	v_mfma_f32_16x16x32_bf16 v[70:73], v[130:133], v[196:199], v[70:73]
	v_mfma_f32_16x16x32_bf16 v[62:65], v[138:141], v[196:199], v[62:65]
	v_mfma_f32_16x16x32_bf16 v[54:57], v[130:133], v[204:207], v[54:57]
	v_mfma_f32_16x16x32_bf16 v[50:53], v[138:141], v[204:207], v[50:53]
	v_mfma_f32_16x16x32_bf16 v[42:45], v[130:133], v[212:215], v[42:45]
	v_mfma_f32_16x16x32_bf16 v[34:37], v[138:141], v[212:215], v[34:37]
	v_mfma_f32_16x16x32_bf16 v[78:81], v[134:137], v[192:195], v[78:81]
	v_mfma_f32_16x16x32_bf16 v[74:77], v[142:145], v[192:195], v[74:77]
	v_mfma_f32_16x16x32_bf16 v[70:73], v[134:137], v[200:203], v[70:73]
	v_mfma_f32_16x16x32_bf16 v[62:65], v[142:145], v[200:203], v[62:65]
	v_mfma_f32_16x16x32_bf16 v[54:57], v[134:137], v[208:211], v[54:57]
	v_mfma_f32_16x16x32_bf16 v[50:53], v[142:145], v[208:211], v[50:53]
	v_mfma_f32_16x16x32_bf16 v[42:45], v[134:137], v[242:245], v[42:45]
	v_mfma_f32_16x16x32_bf16 v[34:37], v[142:145], v[242:245], v[34:37]
	s_setprio 0
	s_setprio 1
	v_mfma_f32_16x16x32_bf16 v[126:129], v[146:149], v[188:191], v[126:129]
	v_mfma_f32_16x16x32_bf16 v[122:125], v[180:183], v[188:191], v[122:125]
	v_mfma_f32_16x16x32_bf16 v[118:121], v[146:149], v[196:199], v[118:121]
	v_mfma_f32_16x16x32_bf16 v[114:117], v[180:183], v[196:199], v[114:117]
	v_mfma_f32_16x16x32_bf16 v[110:113], v[146:149], v[204:207], v[110:113]
	v_mfma_f32_16x16x32_bf16 v[106:109], v[180:183], v[204:207], v[106:109]
	v_mfma_f32_16x16x32_bf16 v[102:105], v[146:149], v[212:215], v[102:105]
	v_mfma_f32_16x16x32_bf16 v[98:101], v[180:183], v[212:215], v[98:101]
	v_mfma_f32_16x16x32_bf16 v[126:129], v[174:177], v[192:195], v[126:129]
	v_mfma_f32_16x16x32_bf16 v[122:125], v[184:187], v[192:195], v[122:125]
	v_mfma_f32_16x16x32_bf16 v[118:121], v[174:177], v[200:203], v[118:121]
	v_mfma_f32_16x16x32_bf16 v[114:117], v[184:187], v[200:203], v[114:117]
	v_mfma_f32_16x16x32_bf16 v[110:113], v[174:177], v[208:211], v[110:113]
	v_mfma_f32_16x16x32_bf16 v[106:109], v[184:187], v[208:211], v[106:109]
	v_mfma_f32_16x16x32_bf16 v[102:105], v[174:177], v[242:245], v[102:105]
	v_mfma_f32_16x16x32_bf16 v[98:101], v[184:187], v[242:245], v[98:101]
	s_barrier
	s_setprio 0
	s_add_i32 s24, s54, s28
	v_lshl_add_u64 v[170:171], v[170:171], 0, s[94:95]
	s_mov_b32 m0, s24
	ds_read_b128 v[188:191], v179 offset:49152
	ds_read_b128 v[192:195], v179 offset:50176
	ds_read_b128 v[196:199], v179 offset:51200
	ds_read_b128 v[200:203], v179 offset:52224
	ds_read_b128 v[204:207], v179 offset:53248
	ds_read_b128 v[208:211], v179 offset:54272
	ds_read_b128 v[212:215], v179 offset:55296
	ds_read_b128 v[242:245], v179 offset:56320
	global_load_lds_dwordx4 v[170:171], off
	s_add_i32 m0, s24, 0x2000
	s_add_u32 s22, s22, 0x40080
	v_lshl_add_u64 v[170:171], v[226:227], 0, s[94:95]
	s_addc_u32 s23, s23, 0
	s_add_i32 s24, s55, s28
	global_load_lds_dwordx4 v[170:171], off
	v_lshl_add_u64 v[170:171], s[22:23], 0, v[154:155]
	s_mov_b32 m0, s24
	s_nop 0
	global_load_lds_dwordx4 v[170:171], off
	v_lshl_add_u64 v[170:171], s[22:23], 0, v[150:151]
	s_add_i32 m0, s24, 0x2000
	s_nop 0
	global_load_lds_dwordx4 v[170:171], off
	v_lshl_add_u64 v[170:171], v[246:247], 0, s[94:95]
	s_mov_b32 m0, s46
	s_nop 0
	global_load_lds_dwordx4 v[170:171], off
	v_lshl_add_u64 v[170:171], v[228:229], 0, s[94:95]
	s_mov_b32 m0, s47
	s_nop 0
	global_load_lds_dwordx4 v[170:171], off
	s_waitcnt vmcnt(8)
	s_waitcnt lgkmcnt(0)
	s_setprio 1
	s_barrier
	s_waitcnt lgkmcnt(0)
	v_mfma_f32_16x16x32_bf16 v[30:33], v[130:133], v[188:191], v[30:33]
	v_mfma_f32_16x16x32_bf16 v[26:29], v[138:141], v[188:191], v[26:29]
	v_mfma_f32_16x16x32_bf16 v[22:25], v[130:133], v[196:199], v[22:25]
	v_mfma_f32_16x16x32_bf16 v[18:21], v[138:141], v[196:199], v[18:21]
	v_mfma_f32_16x16x32_bf16 v[14:17], v[130:133], v[204:207], v[14:17]
	v_mfma_f32_16x16x32_bf16 v[10:13], v[138:141], v[204:207], v[10:13]
	v_mfma_f32_16x16x32_bf16 v[6:9], v[130:133], v[212:215], v[6:9]
	v_mfma_f32_16x16x32_bf16 v[2:5], v[138:141], v[212:215], v[2:5]
	v_mfma_f32_16x16x32_bf16 v[30:33], v[134:137], v[192:195], v[30:33]
	v_mfma_f32_16x16x32_bf16 v[26:29], v[142:145], v[192:195], v[26:29]
	v_mfma_f32_16x16x32_bf16 v[22:25], v[134:137], v[200:203], v[22:25]
	v_mfma_f32_16x16x32_bf16 v[18:21], v[142:145], v[200:203], v[18:21]
	v_mfma_f32_16x16x32_bf16 v[14:17], v[134:137], v[208:211], v[14:17]
	v_mfma_f32_16x16x32_bf16 v[10:13], v[142:145], v[208:211], v[10:13]
	v_mfma_f32_16x16x32_bf16 v[6:9], v[134:137], v[242:245], v[6:9]
	v_mfma_f32_16x16x32_bf16 v[2:5], v[142:145], v[242:245], v[2:5]
	s_setprio 0
	s_setprio 1
	v_mfma_f32_16x16x32_bf16 v[94:97], v[146:149], v[188:191], v[94:97]
	v_mfma_f32_16x16x32_bf16 v[90:93], v[180:183], v[188:191], v[90:93]
	v_mfma_f32_16x16x32_bf16 v[86:89], v[146:149], v[196:199], v[86:89]
	v_mfma_f32_16x16x32_bf16 v[82:85], v[180:183], v[196:199], v[82:85]
	v_mfma_f32_16x16x32_bf16 v[66:69], v[146:149], v[204:207], v[66:69]
	v_mfma_f32_16x16x32_bf16 v[58:61], v[180:183], v[204:207], v[58:61]
	v_mfma_f32_16x16x32_bf16 v[46:49], v[146:149], v[212:215], v[46:49]
	v_mfma_f32_16x16x32_bf16 v[38:41], v[180:183], v[212:215], v[38:41]
	v_mfma_f32_16x16x32_bf16 v[94:97], v[174:177], v[192:195], v[94:97]
	v_mfma_f32_16x16x32_bf16 v[90:93], v[184:187], v[192:195], v[90:93]
	v_mfma_f32_16x16x32_bf16 v[86:89], v[174:177], v[200:203], v[86:89]
	v_mfma_f32_16x16x32_bf16 v[82:85], v[184:187], v[200:203], v[82:85]
	v_mfma_f32_16x16x32_bf16 v[66:69], v[174:177], v[208:211], v[66:69]
	v_mfma_f32_16x16x32_bf16 v[58:61], v[184:187], v[208:211], v[58:61]
	v_mfma_f32_16x16x32_bf16 v[46:49], v[174:177], v[242:245], v[46:49]
	v_mfma_f32_16x16x32_bf16 v[38:41], v[184:187], v[242:245], v[38:41]
	s_barrier
	s_setprio 0
	s_add_i32 s53, s53, 2
	s_add_u32 s4, s4, 0x100
	s_addc_u32 s5, s5, 0
	s_add_u32 s51, s51, 0x100
	s_addc_u32 s52, s52, 0
	s_cmp_gt_u32 s53, 13
	s_cbranch_scc0 .LBB0_174
	s_and_b64 vcc, exec, s[10:11]
	s_cbranch_vccz .LBB0_177
	s_barrier

.LBB0_212:
	s_add_u32 s20, s18, 0xfffc0080
	s_addc_u32 s21, s19, -1
	s_add_i32 s41, 0, 0x10000
	s_cmp_eq_u32 s40, 12
	s_cselect_b32 s23, s13, s21
	s_cselect_b32 s22, s36, s20
	v_add_u32_e32 v142, s41, v145
	s_cselect_b32 s21, s11, s39
	s_cselect_b32 s20, s37, s38
	s_add_i32 s44, 0, 0x14000
	ds_read_b128 v[150:153], v142
	ds_read_b128 v[154:157], v142 offset:1024
	ds_read_b128 v[164:167], v142 offset:2048
	ds_read_b128 v[168:171], v142 offset:3072
	v_add_u32_e32 v142, s44, v145
	ds_read_b128 v[172:175], v142
	ds_read_b128 v[176:179], v142 offset:1024
	ds_read_b128 v[180:183], v142 offset:2048
	ds_read_b128 v[184:187], v142 offset:3072
	v_lshl_add_u64 v[146:147], s[18:19], 0, v[138:139]
	s_add_i32 m0, s25, 0xc000
	ds_read_b128 v[188:191], v149
	ds_read_b128 v[192:195], v149 offset:1024
	ds_read_b128 v[196:199], v149 offset:2048
	ds_read_b128 v[200:203], v149 offset:3072
	ds_read_b128 v[204:207], v149 offset:4096
	ds_read_b128 v[208:211], v149 offset:5120
	ds_read_b128 v[212:215], v149 offset:6144
	ds_read_b128 v[242:245], v149 offset:7168
	global_load_lds_dwordx4 v[146:147], off
	v_lshl_add_u64 v[146:147], s[18:19], 0, v[140:141]
	s_add_i32 m0, s25, 0xe000
	s_nop 0
	global_load_lds_dwordx4 v[146:147], off
	s_waitcnt vmcnt(8)
	s_waitcnt lgkmcnt(0)
	s_setprio 1
	s_barrier
	s_waitcnt lgkmcnt(0)
	v_mfma_f32_16x16x32_bf16 v[126:129], v[150:153], v[188:191], v[126:129]
	v_mfma_f32_16x16x32_bf16 v[122:125], v[164:167], v[188:191], v[122:125]
	v_mfma_f32_16x16x32_bf16 v[114:117], v[150:153], v[196:199], v[114:117]
	v_mfma_f32_16x16x32_bf16 v[106:109], v[164:167], v[196:199], v[106:109]
	v_mfma_f32_16x16x32_bf16 v[98:101], v[150:153], v[204:207], v[98:101]
	v_mfma_f32_16x16x32_bf16 v[90:93], v[164:167], v[204:207], v[90:93]
	v_mfma_f32_16x16x32_bf16 v[82:85], v[150:153], v[212:215], v[82:85]
	v_mfma_f32_16x16x32_bf16 v[74:77], v[164:167], v[212:215], v[74:77]
	v_mfma_f32_16x16x32_bf16 v[126:129], v[154:157], v[192:195], v[126:129]
	v_mfma_f32_16x16x32_bf16 v[122:125], v[168:171], v[192:195], v[122:125]
	v_mfma_f32_16x16x32_bf16 v[114:117], v[154:157], v[200:203], v[114:117]
	v_mfma_f32_16x16x32_bf16 v[106:109], v[168:171], v[200:203], v[106:109]
	v_mfma_f32_16x16x32_bf16 v[98:101], v[154:157], v[208:211], v[98:101]
	v_mfma_f32_16x16x32_bf16 v[90:93], v[168:171], v[208:211], v[90:93]
	v_mfma_f32_16x16x32_bf16 v[82:85], v[154:157], v[242:245], v[82:85]
	v_mfma_f32_16x16x32_bf16 v[74:77], v[168:171], v[242:245], v[74:77]
	s_setprio 0
	s_setprio 1
	v_mfma_f32_16x16x32_bf16 v[118:121], v[172:175], v[188:191], v[118:121]
	v_mfma_f32_16x16x32_bf16 v[110:113], v[180:183], v[188:191], v[110:113]
	v_mfma_f32_16x16x32_bf16 v[102:105], v[172:175], v[196:199], v[102:105]
	v_mfma_f32_16x16x32_bf16 v[94:97], v[180:183], v[196:199], v[94:97]
	v_mfma_f32_16x16x32_bf16 v[86:89], v[172:175], v[204:207], v[86:89]
	v_mfma_f32_16x16x32_bf16 v[78:81], v[180:183], v[204:207], v[78:81]
	v_mfma_f32_16x16x32_bf16 v[70:73], v[172:175], v[212:215], v[70:73]
	v_mfma_f32_16x16x32_bf16 v[66:69], v[180:183], v[212:215], v[66:69]
	v_mfma_f32_16x16x32_bf16 v[118:121], v[176:179], v[192:195], v[118:121]
	v_mfma_f32_16x16x32_bf16 v[110:113], v[184:187], v[192:195], v[110:113]
	v_mfma_f32_16x16x32_bf16 v[102:105], v[176:179], v[200:203], v[102:105]
	v_mfma_f32_16x16x32_bf16 v[94:97], v[184:187], v[200:203], v[94:97]
	v_mfma_f32_16x16x32_bf16 v[86:89], v[176:179], v[208:211], v[86:89]
	v_mfma_f32_16x16x32_bf16 v[78:81], v[184:187], v[208:211], v[78:81]
	v_mfma_f32_16x16x32_bf16 v[70:73], v[176:179], v[242:245], v[70:73]
	v_mfma_f32_16x16x32_bf16 v[66:69], v[184:187], v[242:245], v[66:69]
	s_barrier
	s_setprio 0
	s_add_i32 s41, s41, s24
	v_lshl_add_u64 v[146:147], s[20:21], 0, v[134:135]
	s_mov_b32 m0, s41
	ds_read_b128 v[188:191], v149 offset:16384
	ds_read_b128 v[192:195], v149 offset:17408
	ds_read_b128 v[196:199], v149 offset:18432
	ds_read_b128 v[200:203], v149 offset:19456
	ds_read_b128 v[204:207], v149 offset:20480
	ds_read_b128 v[208:211], v149 offset:21504
	ds_read_b128 v[212:215], v149 offset:22528
	ds_read_b128 v[242:245], v149 offset:23552
	global_load_lds_dwordx4 v[146:147], off
	s_add_i32 m0, s41, 0x2000
	s_add_u32 s42, s20, 0x40000
	v_lshl_add_u64 v[158:159], s[20:21], 0, v[130:131]
	s_addc_u32 s43, s21, 0
	s_add_i32 s41, s44, s24
	global_load_lds_dwordx4 v[158:159], off
	v_lshl_add_u64 v[226:227], s[42:43], 0, v[134:135]
	s_mov_b32 m0, s41
	v_lshl_add_u64 v[228:229], s[22:23], 0, v[132:133]
	global_load_lds_dwordx4 v[226:227], off
	v_lshl_add_u64 v[226:227], s[42:43], 0, v[130:131]
	s_add_i32 m0, s41, 0x2000
	s_nop 0
	global_load_lds_dwordx4 v[226:227], off
	v_lshl_add_u64 v[226:227], s[22:23], 0, v[136:137]
	s_mov_b32 m0, s25
	s_nop 0
	global_load_lds_dwordx4 v[226:227], off
	s_mov_b32 m0, s26
	s_nop 0
	global_load_lds_dwordx4 v[228:229], off
	s_waitcnt vmcnt(8)
	s_waitcnt lgkmcnt(0)
	s_setprio 1
	s_barrier
	s_waitcnt lgkmcnt(0)
	v_mfma_f32_16x16x32_bf16 v[62:65], v[150:153], v[188:191], v[62:65]
	v_mfma_f32_16x16x32_bf16 v[58:61], v[164:167], v[188:191], v[58:61]
	v_mfma_f32_16x16x32_bf16 v[50:53], v[150:153], v[196:199], v[50:53]
	v_mfma_f32_16x16x32_bf16 v[42:45], v[164:167], v[196:199], v[42:45]
	v_mfma_f32_16x16x32_bf16 v[34:37], v[150:153], v[204:207], v[34:37]
	v_mfma_f32_16x16x32_bf16 v[26:29], v[164:167], v[204:207], v[26:29]
	v_mfma_f32_16x16x32_bf16 v[18:21], v[150:153], v[212:215], v[18:21]
	v_mfma_f32_16x16x32_bf16 v[10:13], v[164:167], v[212:215], v[10:13]
	v_mfma_f32_16x16x32_bf16 v[62:65], v[154:157], v[192:195], v[62:65]
	v_mfma_f32_16x16x32_bf16 v[58:61], v[168:171], v[192:195], v[58:61]
	v_mfma_f32_16x16x32_bf16 v[50:53], v[154:157], v[200:203], v[50:53]
	v_mfma_f32_16x16x32_bf16 v[42:45], v[168:171], v[200:203], v[42:45]
	v_mfma_f32_16x16x32_bf16 v[34:37], v[154:157], v[208:211], v[34:37]
	v_mfma_f32_16x16x32_bf16 v[26:29], v[168:171], v[208:211], v[26:29]
	v_mfma_f32_16x16x32_bf16 v[18:21], v[154:157], v[242:245], v[18:21]
	v_mfma_f32_16x16x32_bf16 v[10:13], v[168:171], v[242:245], v[10:13]
	s_setprio 0
	s_setprio 1
	v_mfma_f32_16x16x32_bf16 v[54:57], v[172:175], v[188:191], v[54:57]
	v_mfma_f32_16x16x32_bf16 v[46:49], v[180:183], v[188:191], v[46:49]
	v_mfma_f32_16x16x32_bf16 v[38:41], v[172:175], v[196:199], v[38:41]
	v_mfma_f32_16x16x32_bf16 v[30:33], v[180:183], v[196:199], v[30:33]
	v_mfma_f32_16x16x32_bf16 v[22:25], v[172:175], v[204:207], v[22:25]
	v_mfma_f32_16x16x32_bf16 v[14:17], v[180:183], v[204:207], v[14:17]
	v_mfma_f32_16x16x32_bf16 v[6:9], v[172:175], v[212:215], v[6:9]
	v_mfma_f32_16x16x32_bf16 v[2:5], v[180:183], v[212:215], v[2:5]
	v_mfma_f32_16x16x32_bf16 v[54:57], v[176:179], v[192:195], v[54:57]
	v_mfma_f32_16x16x32_bf16 v[46:49], v[184:187], v[192:195], v[46:49]
	v_mfma_f32_16x16x32_bf16 v[38:41], v[176:179], v[200:203], v[38:41]
	v_mfma_f32_16x16x32_bf16 v[30:33], v[184:187], v[200:203], v[30:33]
	v_mfma_f32_16x16x32_bf16 v[22:25], v[176:179], v[208:211], v[22:25]
	v_mfma_f32_16x16x32_bf16 v[14:17], v[184:187], v[208:211], v[14:17]
	v_mfma_f32_16x16x32_bf16 v[6:9], v[176:179], v[242:245], v[6:9]
	v_mfma_f32_16x16x32_bf16 v[2:5], v[184:187], v[242:245], v[2:5]
	s_barrier
	s_setprio 0
	s_add_i32 s41, 0, 0x18000
	v_add_u32_e32 v142, s41, v145
	s_add_i32 s42, 0, 0x1c000
	ds_read_b128 v[150:153], v142
	ds_read_b128 v[154:157], v142 offset:1024
	ds_read_b128 v[164:167], v142 offset:2048
	ds_read_b128 v[168:171], v142 offset:3072
	v_add_u32_e32 v142, s42, v145
	ds_read_b128 v[172:175], v142
	ds_read_b128 v[176:179], v142 offset:1024
	ds_read_b128 v[180:183], v142 offset:2048
	ds_read_b128 v[184:187], v142 offset:3072
	s_add_u32 s22, s22, 0x40000
	s_addc_u32 s23, s23, 0
	s_mov_b32 m0, s27
	v_lshl_add_u64 v[230:231], s[22:23], 0, v[136:137]
	ds_read_b128 v[188:191], v149 offset:32768
	ds_read_b128 v[192:195], v149 offset:33792
	ds_read_b128 v[196:199], v149 offset:34816
	ds_read_b128 v[200:203], v149 offset:35840
	ds_read_b128 v[204:207], v149 offset:36864
	ds_read_b128 v[208:211], v149 offset:37888
	ds_read_b128 v[212:215], v149 offset:38912
	ds_read_b128 v[242:245], v149 offset:39936
	global_load_lds_dwordx4 v[230:231], off
	v_lshl_add_u64 v[230:231], s[22:23], 0, v[132:133]
	s_mov_b32 m0, s28
	s_nop 0
	global_load_lds_dwordx4 v[230:231], off
	s_waitcnt vmcnt(8)
	s_waitcnt lgkmcnt(0)
	s_setprio 1
	s_barrier
	s_waitcnt lgkmcnt(0)
	v_mfma_f32_16x16x32_bf16 v[126:129], v[150:153], v[188:191], v[126:129]
	v_mfma_f32_16x16x32_bf16 v[122:125], v[164:167], v[188:191], v[122:125]
	v_mfma_f32_16x16x32_bf16 v[114:117], v[150:153], v[196:199], v[114:117]
	v_mfma_f32_16x16x32_bf16 v[106:109], v[164:167], v[196:199], v[106:109]
	v_mfma_f32_16x16x32_bf16 v[98:101], v[150:153], v[204:207], v[98:101]
	v_mfma_f32_16x16x32_bf16 v[90:93], v[164:167], v[204:207], v[90:93]
	v_mfma_f32_16x16x32_bf16 v[82:85], v[150:153], v[212:215], v[82:85]
	v_mfma_f32_16x16x32_bf16 v[74:77], v[164:167], v[212:215], v[74:77]
	v_mfma_f32_16x16x32_bf16 v[126:129], v[154:157], v[192:195], v[126:129]
	v_mfma_f32_16x16x32_bf16 v[122:125], v[168:171], v[192:195], v[122:125]
	v_mfma_f32_16x16x32_bf16 v[114:117], v[154:157], v[200:203], v[114:117]
	v_mfma_f32_16x16x32_bf16 v[106:109], v[168:171], v[200:203], v[106:109]
	v_mfma_f32_16x16x32_bf16 v[98:101], v[154:157], v[208:211], v[98:101]
	v_mfma_f32_16x16x32_bf16 v[90:93], v[168:171], v[208:211], v[90:93]
	v_mfma_f32_16x16x32_bf16 v[82:85], v[154:157], v[242:245], v[82:85]
	v_mfma_f32_16x16x32_bf16 v[74:77], v[168:171], v[242:245], v[74:77]
	s_setprio 0
	s_setprio 1
	v_mfma_f32_16x16x32_bf16 v[118:121], v[172:175], v[188:191], v[118:121]
	v_mfma_f32_16x16x32_bf16 v[110:113], v[180:183], v[188:191], v[110:113]
	v_mfma_f32_16x16x32_bf16 v[102:105], v[172:175], v[196:199], v[102:105]
	v_mfma_f32_16x16x32_bf16 v[94:97], v[180:183], v[196:199], v[94:97]
	v_mfma_f32_16x16x32_bf16 v[86:89], v[172:175], v[204:207], v[86:89]
	v_mfma_f32_16x16x32_bf16 v[78:81], v[180:183], v[204:207], v[78:81]
	v_mfma_f32_16x16x32_bf16 v[70:73], v[172:175], v[212:215], v[70:73]
	v_mfma_f32_16x16x32_bf16 v[66:69], v[180:183], v[212:215], v[66:69]
	v_mfma_f32_16x16x32_bf16 v[118:121], v[176:179], v[192:195], v[118:121]
	v_mfma_f32_16x16x32_bf16 v[110:113], v[184:187], v[192:195], v[110:113]
	v_mfma_f32_16x16x32_bf16 v[102:105], v[176:179], v[200:203], v[102:105]
	v_mfma_f32_16x16x32_bf16 v[94:97], v[184:187], v[200:203], v[94:97]
	v_mfma_f32_16x16x32_bf16 v[86:89], v[176:179], v[208:211], v[86:89]
	v_mfma_f32_16x16x32_bf16 v[78:81], v[184:187], v[208:211], v[78:81]
	v_mfma_f32_16x16x32_bf16 v[70:73], v[176:179], v[242:245], v[70:73]
	v_mfma_f32_16x16x32_bf16 v[66:69], v[184:187], v[242:245], v[66:69]
	s_barrier
	s_setprio 0
	s_add_i32 s22, s41, s24
	v_lshl_add_u64 v[146:147], v[146:147], 0, s[94:95]
	s_mov_b32 m0, s22
	ds_read_b128 v[188:191], v149 offset:49152
	ds_read_b128 v[192:195], v149 offset:50176
	ds_read_b128 v[196:199], v149 offset:51200
	ds_read_b128 v[200:203], v149 offset:52224
	ds_read_b128 v[204:207], v149 offset:53248
	ds_read_b128 v[208:211], v149 offset:54272
	ds_read_b128 v[212:215], v149 offset:55296
	ds_read_b128 v[242:245], v149 offset:56320
	global_load_lds_dwordx4 v[146:147], off
	s_add_i32 m0, s22, 0x2000
	s_add_u32 s20, s20, 0x40080
	v_lshl_add_u64 v[146:147], v[158:159], 0, s[94:95]
	s_addc_u32 s21, s21, 0
	s_add_i32 s22, s42, s24
	global_load_lds_dwordx4 v[146:147], off
	v_lshl_add_u64 v[146:147], s[20:21], 0, v[134:135]
	s_mov_b32 m0, s22
	s_nop 0
	global_load_lds_dwordx4 v[146:147], off
	v_lshl_add_u64 v[146:147], s[20:21], 0, v[130:131]
	s_add_i32 m0, s22, 0x2000
	s_nop 0
	global_load_lds_dwordx4 v[146:147], off
	v_lshl_add_u64 v[146:147], v[226:227], 0, s[94:95]
	s_mov_b32 m0, s29
	s_nop 0
	global_load_lds_dwordx4 v[146:147], off
	v_lshl_add_u64 v[146:147], v[228:229], 0, s[94:95]
	s_mov_b32 m0, s30
	s_nop 0
	global_load_lds_dwordx4 v[146:147], off
	s_waitcnt vmcnt(8)
	s_waitcnt lgkmcnt(0)
	s_setprio 1
	s_barrier
	s_waitcnt lgkmcnt(0)
	v_mfma_f32_16x16x32_bf16 v[62:65], v[150:153], v[188:191], v[62:65]
	v_mfma_f32_16x16x32_bf16 v[58:61], v[164:167], v[188:191], v[58:61]
	v_mfma_f32_16x16x32_bf16 v[50:53], v[150:153], v[196:199], v[50:53]
	v_mfma_f32_16x16x32_bf16 v[42:45], v[164:167], v[196:199], v[42:45]
	v_mfma_f32_16x16x32_bf16 v[34:37], v[150:153], v[204:207], v[34:37]
	v_mfma_f32_16x16x32_bf16 v[26:29], v[164:167], v[204:207], v[26:29]
	v_mfma_f32_16x16x32_bf16 v[18:21], v[150:153], v[212:215], v[18:21]
	v_mfma_f32_16x16x32_bf16 v[10:13], v[164:167], v[212:215], v[10:13]
	v_mfma_f32_16x16x32_bf16 v[62:65], v[154:157], v[192:195], v[62:65]
	v_mfma_f32_16x16x32_bf16 v[58:61], v[168:171], v[192:195], v[58:61]
	v_mfma_f32_16x16x32_bf16 v[50:53], v[154:157], v[200:203], v[50:53]
	v_mfma_f32_16x16x32_bf16 v[42:45], v[168:171], v[200:203], v[42:45]
	v_mfma_f32_16x16x32_bf16 v[34:37], v[154:157], v[208:211], v[34:37]
	v_mfma_f32_16x16x32_bf16 v[26:29], v[168:171], v[208:211], v[26:29]
	v_mfma_f32_16x16x32_bf16 v[18:21], v[154:157], v[242:245], v[18:21]
	v_mfma_f32_16x16x32_bf16 v[10:13], v[168:171], v[242:245], v[10:13]
	s_setprio 0
	s_setprio 1
	v_mfma_f32_16x16x32_bf16 v[54:57], v[172:175], v[188:191], v[54:57]
	v_mfma_f32_16x16x32_bf16 v[46:49], v[180:183], v[188:191], v[46:49]
	v_mfma_f32_16x16x32_bf16 v[38:41], v[172:175], v[196:199], v[38:41]
	v_mfma_f32_16x16x32_bf16 v[30:33], v[180:183], v[196:199], v[30:33]
	v_mfma_f32_16x16x32_bf16 v[22:25], v[172:175], v[204:207], v[22:25]
	v_mfma_f32_16x16x32_bf16 v[14:17], v[180:183], v[204:207], v[14:17]
	v_mfma_f32_16x16x32_bf16 v[6:9], v[172:175], v[212:215], v[6:9]
	v_mfma_f32_16x16x32_bf16 v[2:5], v[180:183], v[212:215], v[2:5]
	v_mfma_f32_16x16x32_bf16 v[54:57], v[176:179], v[192:195], v[54:57]
	v_mfma_f32_16x16x32_bf16 v[46:49], v[184:187], v[192:195], v[46:49]
	v_mfma_f32_16x16x32_bf16 v[38:41], v[176:179], v[200:203], v[38:41]
	v_mfma_f32_16x16x32_bf16 v[30:33], v[184:187], v[200:203], v[30:33]
	v_mfma_f32_16x16x32_bf16 v[22:25], v[176:179], v[208:211], v[22:25]
	v_mfma_f32_16x16x32_bf16 v[14:17], v[184:187], v[208:211], v[14:17]
	v_mfma_f32_16x16x32_bf16 v[6:9], v[176:179], v[242:245], v[6:9]
	v_mfma_f32_16x16x32_bf16 v[2:5], v[184:187], v[242:245], v[2:5]
	s_barrier
	s_setprio 0
	s_add_i32 s40, s40, 2
	s_add_u32 s18, s18, 0x100
	s_addc_u32 s19, s19, 0
	s_add_u32 s38, s38, 0x100
	s_addc_u32 s39, s39, 0
	s_cmp_gt_u32 s40, 13
	s_cbranch_scc0 .LBB0_212
	v_readlane_b32 s40, v254, 38
	s_and_b64 vcc, exec, s[8:9]
	v_readlane_b32 s36, v254, 2
	v_readlane_b32 s41, v254, 39
	v_readlane_b32 s42, v254, 40
	v_readlane_b32 s43, v254, 41
	v_readlane_b32 s37, v254, 3
	s_cbranch_vccz .LBB0_215
	s_barrier

.LBB0_233:
	s_add_i32 s49, s24, 2
	s_add_u32 s50, s22, 0x80
	s_addc_u32 s25, s23, 0
	s_add_i32 s52, 0, 0x10000
	s_cmp_eq_u32 s42, s24
	s_cselect_b32 s25, s17, s25
	s_cselect_b32 s24, s45, s50
	v_add_u32_e32 v0, s52, v157
	s_cselect_b32 s51, s15, s48
	s_cselect_b32 s50, s46, s47
	s_add_i32 s53, 0, 0x14000
	ds_read_b128 v[126:129], v0
	ds_read_b128 v[134:137], v0 offset:1024
	ds_read_b128 v[138:141], v0 offset:2048
	ds_read_b128 v[142:145], v0 offset:3072
	v_add_u32_e32 v0, s53, v157
	ds_read_b128 v[166:169], v0
	ds_read_b128 v[170:173], v0 offset:1024
	ds_read_b128 v[178:181], v0 offset:2048
	ds_read_b128 v[182:185], v0 offset:3072
	v_lshl_add_u64 v[174:175], s[22:23], 0, v[158:159]
	s_add_i32 m0, s34, 0xc000
	ds_read_b128 v[186:189], v176
	ds_read_b128 v[190:193], v176 offset:1024
	ds_read_b128 v[194:197], v176 offset:2048
	ds_read_b128 v[198:201], v176 offset:3072
	ds_read_b128 v[202:205], v176 offset:4096
	ds_read_b128 v[206:209], v176 offset:5120
	ds_read_b128 v[210:213], v176 offset:6144
	ds_read_b128 v[242:245], v176 offset:7168
	global_load_lds_dwordx4 v[174:175], off
	v_lshl_add_u64 v[174:175], s[22:23], 0, v[164:165]
	s_add_i32 m0, s34, 0xe000
	s_nop 0
	global_load_lds_dwordx4 v[174:175], off
	s_waitcnt vmcnt(8)
	s_waitcnt lgkmcnt(0)
	s_setprio 1
	s_barrier
	s_waitcnt lgkmcnt(0)
	v_mfma_f32_16x16x32_bf16 v[130:133], v[126:129], v[186:189], v[130:133]
	v_mfma_f32_16x16x32_bf16 v[122:125], v[138:141], v[186:189], v[122:125]
	v_mfma_f32_16x16x32_bf16 v[110:113], v[126:129], v[194:197], v[110:113]
	v_mfma_f32_16x16x32_bf16 v[106:109], v[138:141], v[194:197], v[106:109]
	v_mfma_f32_16x16x32_bf16 v[94:97], v[126:129], v[202:205], v[94:97]
	v_mfma_f32_16x16x32_bf16 v[90:93], v[138:141], v[202:205], v[90:93]
	v_mfma_f32_16x16x32_bf16 v[78:81], v[126:129], v[210:213], v[78:81]
	v_mfma_f32_16x16x32_bf16 v[74:77], v[138:141], v[210:213], v[74:77]
	v_mfma_f32_16x16x32_bf16 v[130:133], v[134:137], v[190:193], v[130:133]
	v_mfma_f32_16x16x32_bf16 v[122:125], v[142:145], v[190:193], v[122:125]
	v_mfma_f32_16x16x32_bf16 v[110:113], v[134:137], v[198:201], v[110:113]
	v_mfma_f32_16x16x32_bf16 v[106:109], v[142:145], v[198:201], v[106:109]
	v_mfma_f32_16x16x32_bf16 v[94:97], v[134:137], v[206:209], v[94:97]
	v_mfma_f32_16x16x32_bf16 v[90:93], v[142:145], v[206:209], v[90:93]
	v_mfma_f32_16x16x32_bf16 v[78:81], v[134:137], v[242:245], v[78:81]
	v_mfma_f32_16x16x32_bf16 v[74:77], v[142:145], v[242:245], v[74:77]
	s_setprio 0
	s_setprio 1
	v_mfma_f32_16x16x32_bf16 v[118:121], v[166:169], v[186:189], v[118:121]
	v_mfma_f32_16x16x32_bf16 v[114:117], v[178:181], v[186:189], v[114:117]
	v_mfma_f32_16x16x32_bf16 v[102:105], v[166:169], v[194:197], v[102:105]
	v_mfma_f32_16x16x32_bf16 v[98:101], v[178:181], v[194:197], v[98:101]
	v_mfma_f32_16x16x32_bf16 v[86:89], v[166:169], v[202:205], v[86:89]
	v_mfma_f32_16x16x32_bf16 v[82:85], v[178:181], v[202:205], v[82:85]
	v_mfma_f32_16x16x32_bf16 v[70:73], v[166:169], v[210:213], v[70:73]
	v_mfma_f32_16x16x32_bf16 v[66:69], v[178:181], v[210:213], v[66:69]
	v_mfma_f32_16x16x32_bf16 v[118:121], v[170:173], v[190:193], v[118:121]
	v_mfma_f32_16x16x32_bf16 v[114:117], v[182:185], v[190:193], v[114:117]
	v_mfma_f32_16x16x32_bf16 v[102:105], v[170:173], v[198:201], v[102:105]
	v_mfma_f32_16x16x32_bf16 v[98:101], v[182:185], v[198:201], v[98:101]
	v_mfma_f32_16x16x32_bf16 v[86:89], v[170:173], v[206:209], v[86:89]
	v_mfma_f32_16x16x32_bf16 v[82:85], v[182:185], v[206:209], v[82:85]
	v_mfma_f32_16x16x32_bf16 v[70:73], v[170:173], v[242:245], v[70:73]
	v_mfma_f32_16x16x32_bf16 v[66:69], v[182:185], v[242:245], v[66:69]
	s_barrier
	s_setprio 0
	s_add_i32 s52, s52, s31
	v_lshl_add_u64 v[174:175], s[50:51], 0, v[150:151]
	s_mov_b32 m0, s52
	ds_read_b128 v[186:189], v176 offset:16384
	ds_read_b128 v[190:193], v176 offset:17408
	ds_read_b128 v[194:197], v176 offset:18432
	ds_read_b128 v[198:201], v176 offset:19456
	ds_read_b128 v[202:205], v176 offset:20480
	ds_read_b128 v[206:209], v176 offset:21504
	ds_read_b128 v[210:213], v176 offset:22528
	ds_read_b128 v[242:245], v176 offset:23552
	global_load_lds_dwordx4 v[174:175], off
	s_add_i32 m0, s52, 0x2000
	v_lshl_add_u64 v[214:215], s[50:51], 0, v[146:147]
	s_add_u32 s50, s50, s0
	s_addc_u32 s51, s51, 0
	s_add_i32 s52, s53, s31
	global_load_lds_dwordx4 v[214:215], off
	v_lshl_add_u64 v[226:227], s[50:51], 0, v[150:151]
	s_mov_b32 m0, s52
	v_lshl_add_u64 v[228:229], s[50:51], 0, v[146:147]
	global_load_lds_dwordx4 v[226:227], off
	s_add_i32 m0, s52, 0x2000
	v_lshl_add_u64 v[230:231], s[24:25], 0, v[152:153]
	global_load_lds_dwordx4 v[228:229], off
	s_mov_b32 m0, s34
	v_lshl_add_u64 v[232:233], s[24:25], 0, v[148:149]
	global_load_lds_dwordx4 v[230:231], off
	s_mov_b32 m0, s35
	s_nop 0
	global_load_lds_dwordx4 v[232:233], off
	s_waitcnt vmcnt(8)
	s_waitcnt lgkmcnt(0)
	s_setprio 1
	s_barrier
	s_waitcnt lgkmcnt(0)
	v_mfma_f32_16x16x32_bf16 v[62:65], v[126:129], v[186:189], v[62:65]
	v_mfma_f32_16x16x32_bf16 v[58:61], v[138:141], v[186:189], v[58:61]
	v_mfma_f32_16x16x32_bf16 v[46:49], v[126:129], v[194:197], v[46:49]
	v_mfma_f32_16x16x32_bf16 v[42:45], v[138:141], v[194:197], v[42:45]
	v_mfma_f32_16x16x32_bf16 v[30:33], v[126:129], v[202:205], v[30:33]
	v_mfma_f32_16x16x32_bf16 v[26:29], v[138:141], v[202:205], v[26:29]
	v_mfma_f32_16x16x32_bf16 v[14:17], v[126:129], v[210:213], v[14:17]
	v_mfma_f32_16x16x32_bf16 v[10:13], v[138:141], v[210:213], v[10:13]
	v_mfma_f32_16x16x32_bf16 v[62:65], v[134:137], v[190:193], v[62:65]
	v_mfma_f32_16x16x32_bf16 v[58:61], v[142:145], v[190:193], v[58:61]
	v_mfma_f32_16x16x32_bf16 v[46:49], v[134:137], v[198:201], v[46:49]
	v_mfma_f32_16x16x32_bf16 v[42:45], v[142:145], v[198:201], v[42:45]
	v_mfma_f32_16x16x32_bf16 v[30:33], v[134:137], v[206:209], v[30:33]
	v_mfma_f32_16x16x32_bf16 v[26:29], v[142:145], v[206:209], v[26:29]
	v_mfma_f32_16x16x32_bf16 v[14:17], v[134:137], v[242:245], v[14:17]
	v_mfma_f32_16x16x32_bf16 v[10:13], v[142:145], v[242:245], v[10:13]
	s_setprio 0
	s_setprio 1
	v_mfma_f32_16x16x32_bf16 v[54:57], v[166:169], v[186:189], v[54:57]
	v_mfma_f32_16x16x32_bf16 v[50:53], v[178:181], v[186:189], v[50:53]
	v_mfma_f32_16x16x32_bf16 v[38:41], v[166:169], v[194:197], v[38:41]
	v_mfma_f32_16x16x32_bf16 v[34:37], v[178:181], v[194:197], v[34:37]
	v_mfma_f32_16x16x32_bf16 v[22:25], v[166:169], v[202:205], v[22:25]
	v_mfma_f32_16x16x32_bf16 v[18:21], v[178:181], v[202:205], v[18:21]
	v_mfma_f32_16x16x32_bf16 v[6:9], v[166:169], v[210:213], v[6:9]
	v_mfma_f32_16x16x32_bf16 v[2:5], v[178:181], v[210:213], v[2:5]
	v_mfma_f32_16x16x32_bf16 v[54:57], v[170:173], v[190:193], v[54:57]
	v_mfma_f32_16x16x32_bf16 v[50:53], v[182:185], v[190:193], v[50:53]
	v_mfma_f32_16x16x32_bf16 v[38:41], v[170:173], v[198:201], v[38:41]
	v_mfma_f32_16x16x32_bf16 v[34:37], v[182:185], v[198:201], v[34:37]
	v_mfma_f32_16x16x32_bf16 v[22:25], v[170:173], v[206:209], v[22:25]
	v_mfma_f32_16x16x32_bf16 v[18:21], v[182:185], v[206:209], v[18:21]
	v_mfma_f32_16x16x32_bf16 v[6:9], v[170:173], v[242:245], v[6:9]
	v_mfma_f32_16x16x32_bf16 v[2:5], v[182:185], v[242:245], v[2:5]
	s_barrier
	s_setprio 0
	s_add_i32 s50, 0, 0x18000
	v_add_u32_e32 v0, s50, v157
	s_add_i32 s51, 0, 0x1c000
	ds_read_b128 v[126:129], v0
	ds_read_b128 v[134:137], v0 offset:1024
	ds_read_b128 v[138:141], v0 offset:2048
	ds_read_b128 v[142:145], v0 offset:3072
	v_add_u32_e32 v0, s51, v157
	ds_read_b128 v[166:169], v0
	ds_read_b128 v[170:173], v0 offset:1024
	ds_read_b128 v[178:181], v0 offset:2048
	ds_read_b128 v[182:185], v0 offset:3072
	s_add_u32 s24, s24, s0
	s_addc_u32 s25, s25, 0
	s_mov_b32 m0, s36
	v_lshl_add_u64 v[246:247], s[24:25], 0, v[152:153]
	ds_read_b128 v[186:189], v176 offset:32768
	ds_read_b128 v[190:193], v176 offset:33792
	ds_read_b128 v[194:197], v176 offset:34816
	ds_read_b128 v[198:201], v176 offset:35840
	ds_read_b128 v[202:205], v176 offset:36864
	ds_read_b128 v[206:209], v176 offset:37888
	ds_read_b128 v[210:213], v176 offset:38912
	ds_read_b128 v[242:245], v176 offset:39936
	global_load_lds_dwordx4 v[246:247], off
	v_lshl_add_u64 v[246:247], s[24:25], 0, v[148:149]
	s_mov_b32 m0, s37
	s_nop 0
	global_load_lds_dwordx4 v[246:247], off
	s_waitcnt vmcnt(8)
	s_waitcnt lgkmcnt(0)
	s_setprio 1
	s_barrier
	s_waitcnt lgkmcnt(0)
	v_mfma_f32_16x16x32_bf16 v[130:133], v[126:129], v[186:189], v[130:133]
	v_mfma_f32_16x16x32_bf16 v[122:125], v[138:141], v[186:189], v[122:125]
	v_mfma_f32_16x16x32_bf16 v[110:113], v[126:129], v[194:197], v[110:113]
	v_mfma_f32_16x16x32_bf16 v[106:109], v[138:141], v[194:197], v[106:109]
	v_mfma_f32_16x16x32_bf16 v[94:97], v[126:129], v[202:205], v[94:97]
	v_mfma_f32_16x16x32_bf16 v[90:93], v[138:141], v[202:205], v[90:93]
	v_mfma_f32_16x16x32_bf16 v[78:81], v[126:129], v[210:213], v[78:81]
	v_mfma_f32_16x16x32_bf16 v[74:77], v[138:141], v[210:213], v[74:77]
	v_mfma_f32_16x16x32_bf16 v[130:133], v[134:137], v[190:193], v[130:133]
	v_mfma_f32_16x16x32_bf16 v[122:125], v[142:145], v[190:193], v[122:125]
	v_mfma_f32_16x16x32_bf16 v[110:113], v[134:137], v[198:201], v[110:113]
	v_mfma_f32_16x16x32_bf16 v[106:109], v[142:145], v[198:201], v[106:109]
	v_mfma_f32_16x16x32_bf16 v[94:97], v[134:137], v[206:209], v[94:97]
	v_mfma_f32_16x16x32_bf16 v[90:93], v[142:145], v[206:209], v[90:93]
	v_mfma_f32_16x16x32_bf16 v[78:81], v[134:137], v[242:245], v[78:81]
	v_mfma_f32_16x16x32_bf16 v[74:77], v[142:145], v[242:245], v[74:77]
	s_setprio 0
	s_setprio 1
	v_mfma_f32_16x16x32_bf16 v[118:121], v[166:169], v[186:189], v[118:121]
	v_mfma_f32_16x16x32_bf16 v[114:117], v[178:181], v[186:189], v[114:117]
	v_mfma_f32_16x16x32_bf16 v[102:105], v[166:169], v[194:197], v[102:105]
	v_mfma_f32_16x16x32_bf16 v[98:101], v[178:181], v[194:197], v[98:101]
	v_mfma_f32_16x16x32_bf16 v[86:89], v[166:169], v[202:205], v[86:89]
	v_mfma_f32_16x16x32_bf16 v[82:85], v[178:181], v[202:205], v[82:85]
	v_mfma_f32_16x16x32_bf16 v[70:73], v[166:169], v[210:213], v[70:73]
	v_mfma_f32_16x16x32_bf16 v[66:69], v[178:181], v[210:213], v[66:69]
	v_mfma_f32_16x16x32_bf16 v[118:121], v[170:173], v[190:193], v[118:121]
	v_mfma_f32_16x16x32_bf16 v[114:117], v[182:185], v[190:193], v[114:117]
	v_mfma_f32_16x16x32_bf16 v[102:105], v[170:173], v[198:201], v[102:105]
	v_mfma_f32_16x16x32_bf16 v[98:101], v[182:185], v[198:201], v[98:101]
	v_mfma_f32_16x16x32_bf16 v[86:89], v[170:173], v[206:209], v[86:89]
	v_mfma_f32_16x16x32_bf16 v[82:85], v[182:185], v[206:209], v[82:85]
	v_mfma_f32_16x16x32_bf16 v[70:73], v[170:173], v[242:245], v[70:73]
	v_mfma_f32_16x16x32_bf16 v[66:69], v[182:185], v[242:245], v[66:69]
	s_barrier
	s_setprio 0
	s_add_i32 s24, s50, s31
	v_lshl_add_u64 v[174:175], v[174:175], 0, s[94:95]
	s_mov_b32 m0, s24
	ds_read_b128 v[186:189], v176 offset:49152
	ds_read_b128 v[190:193], v176 offset:50176
	ds_read_b128 v[194:197], v176 offset:51200
	ds_read_b128 v[198:201], v176 offset:52224
	ds_read_b128 v[202:205], v176 offset:53248
	ds_read_b128 v[206:209], v176 offset:54272
	ds_read_b128 v[210:213], v176 offset:55296
	ds_read_b128 v[242:245], v176 offset:56320
	global_load_lds_dwordx4 v[174:175], off
	v_lshl_add_u64 v[174:175], v[214:215], 0, s[94:95]
	s_add_i32 m0, s24, 0x2000
	s_add_i32 s24, s51, s31
	global_load_lds_dwordx4 v[174:175], off
	v_lshl_add_u64 v[174:175], v[226:227], 0, s[94:95]
	s_mov_b32 m0, s24
	s_nop 0
	global_load_lds_dwordx4 v[174:175], off
	v_lshl_add_u64 v[174:175], v[228:229], 0, s[94:95]
	s_add_i32 m0, s24, 0x2000
	s_nop 0
	global_load_lds_dwordx4 v[174:175], off
	v_lshl_add_u64 v[174:175], v[230:231], 0, s[94:95]
	s_mov_b32 m0, s38
	s_nop 0
	global_load_lds_dwordx4 v[174:175], off
	v_lshl_add_u64 v[174:175], v[232:233], 0, s[94:95]
	s_mov_b32 m0, s39
	s_nop 0
	global_load_lds_dwordx4 v[174:175], off
	s_waitcnt vmcnt(8)
	s_waitcnt lgkmcnt(0)
	s_setprio 1
	s_barrier
	s_waitcnt lgkmcnt(0)
	v_mfma_f32_16x16x32_bf16 v[62:65], v[126:129], v[186:189], v[62:65]
	v_mfma_f32_16x16x32_bf16 v[58:61], v[138:141], v[186:189], v[58:61]
	v_mfma_f32_16x16x32_bf16 v[46:49], v[126:129], v[194:197], v[46:49]
	v_mfma_f32_16x16x32_bf16 v[42:45], v[138:141], v[194:197], v[42:45]
	v_mfma_f32_16x16x32_bf16 v[30:33], v[126:129], v[202:205], v[30:33]
	v_mfma_f32_16x16x32_bf16 v[26:29], v[138:141], v[202:205], v[26:29]
	v_mfma_f32_16x16x32_bf16 v[14:17], v[126:129], v[210:213], v[14:17]
	v_mfma_f32_16x16x32_bf16 v[10:13], v[138:141], v[210:213], v[10:13]
	v_mfma_f32_16x16x32_bf16 v[62:65], v[134:137], v[190:193], v[62:65]
	v_mfma_f32_16x16x32_bf16 v[58:61], v[142:145], v[190:193], v[58:61]
	v_mfma_f32_16x16x32_bf16 v[46:49], v[134:137], v[198:201], v[46:49]
	v_mfma_f32_16x16x32_bf16 v[42:45], v[142:145], v[198:201], v[42:45]
	v_mfma_f32_16x16x32_bf16 v[30:33], v[134:137], v[206:209], v[30:33]
	v_mfma_f32_16x16x32_bf16 v[26:29], v[142:145], v[206:209], v[26:29]
	v_mfma_f32_16x16x32_bf16 v[14:17], v[134:137], v[242:245], v[14:17]
	v_mfma_f32_16x16x32_bf16 v[10:13], v[142:145], v[242:245], v[10:13]
	s_setprio 0
	s_setprio 1
	v_mfma_f32_16x16x32_bf16 v[54:57], v[166:169], v[186:189], v[54:57]
	v_mfma_f32_16x16x32_bf16 v[50:53], v[178:181], v[186:189], v[50:53]
	v_mfma_f32_16x16x32_bf16 v[38:41], v[166:169], v[194:197], v[38:41]
	v_mfma_f32_16x16x32_bf16 v[34:37], v[178:181], v[194:197], v[34:37]
	v_mfma_f32_16x16x32_bf16 v[22:25], v[166:169], v[202:205], v[22:25]
	v_mfma_f32_16x16x32_bf16 v[18:21], v[178:181], v[202:205], v[18:21]
	v_mfma_f32_16x16x32_bf16 v[6:9], v[166:169], v[210:213], v[6:9]
	v_mfma_f32_16x16x32_bf16 v[2:5], v[178:181], v[210:213], v[2:5]
	v_mfma_f32_16x16x32_bf16 v[54:57], v[170:173], v[190:193], v[54:57]
	v_mfma_f32_16x16x32_bf16 v[50:53], v[182:185], v[190:193], v[50:53]
	v_mfma_f32_16x16x32_bf16 v[38:41], v[170:173], v[198:201], v[38:41]
	v_mfma_f32_16x16x32_bf16 v[34:37], v[182:185], v[198:201], v[34:37]
	v_mfma_f32_16x16x32_bf16 v[22:25], v[170:173], v[206:209], v[22:25]
	v_mfma_f32_16x16x32_bf16 v[18:21], v[182:185], v[206:209], v[18:21]
	v_mfma_f32_16x16x32_bf16 v[6:9], v[170:173], v[242:245], v[6:9]
	v_mfma_f32_16x16x32_bf16 v[2:5], v[182:185], v[242:245], v[2:5]
	s_barrier
	s_setprio 0
	s_add_u32 s22, s22, 0x100
	s_addc_u32 s23, s23, 0
	s_add_u32 s47, s47, 0x100
	s_addc_u32 s48, s48, 0
	s_cmp_ge_u32 s49, s40
	s_mov_b32 s24, s49
	s_cbranch_scc0 .LBB0_233
	s_and_b64 vcc, exec, s[12:13]
	s_cbranch_vccz .LBB0_236
	s_barrier

.LBB0_402:
	s_add_i32 s53, s8, 2
	s_add_u32 s54, s0, 0xfffc0080
	s_addc_u32 s9, s1, -1
	s_add_i32 s56, 0, 0x10000
	s_cmp_eq_u32 s47, s8
	s_cselect_b32 s9, s27, s9
	s_cselect_b32 s8, s52, s54
	v_add_u32_e32 v0, s56, v141
	s_cselect_b32 s55, s29, s35
	s_cselect_b32 s54, s28, s34
	s_add_i32 s57, 0, 0x14000
	ds_read_b128 v[148:151], v0
	ds_read_b128 v[152:155], v0 offset:1024
	ds_read_b128 v[156:159], v0 offset:2048
	ds_read_b128 v[164:167], v0 offset:3072
	v_add_u32_e32 v0, s57, v141
	ds_read_b128 v[168:171], v0
	ds_read_b128 v[172:175], v0 offset:1024
	ds_read_b128 v[176:179], v0 offset:2048
	ds_read_b128 v[180:183], v0 offset:3072
	v_lshl_add_u64 v[226:227], s[0:1], 0, v[142:143]
	s_add_i32 m0, s40, 0xc000
	ds_read_b128 v[184:187], v147
	ds_read_b128 v[188:191], v147 offset:1024
	ds_read_b128 v[192:195], v147 offset:2048
	ds_read_b128 v[196:199], v147 offset:3072
	ds_read_b128 v[200:203], v147 offset:4096
	ds_read_b128 v[204:207], v147 offset:5120
	ds_read_b128 v[208:211], v147 offset:6144
	ds_read_b128 v[212:215], v147 offset:7168
	global_load_lds_dwordx4 v[226:227], off
	v_lshl_add_u64 v[226:227], s[0:1], 0, v[144:145]
	s_add_i32 m0, s40, 0xe000
	s_nop 0
	global_load_lds_dwordx4 v[226:227], off
	s_waitcnt vmcnt(8)
	s_waitcnt lgkmcnt(0)
	s_setprio 1
	s_barrier
	s_waitcnt lgkmcnt(0)
	v_mfma_f32_16x16x32_bf16 v[126:129], v[148:151], v[184:187], v[126:129]
	v_mfma_f32_16x16x32_bf16 v[122:125], v[156:159], v[184:187], v[122:125]
	v_mfma_f32_16x16x32_bf16 v[110:113], v[148:151], v[192:195], v[110:113]
	v_mfma_f32_16x16x32_bf16 v[106:109], v[156:159], v[192:195], v[106:109]
	v_mfma_f32_16x16x32_bf16 v[94:97], v[148:151], v[200:203], v[94:97]
	v_mfma_f32_16x16x32_bf16 v[90:93], v[156:159], v[200:203], v[90:93]
	v_mfma_f32_16x16x32_bf16 v[78:81], v[148:151], v[208:211], v[78:81]
	v_mfma_f32_16x16x32_bf16 v[74:77], v[156:159], v[208:211], v[74:77]
	v_mfma_f32_16x16x32_bf16 v[126:129], v[152:155], v[188:191], v[126:129]
	v_mfma_f32_16x16x32_bf16 v[122:125], v[164:167], v[188:191], v[122:125]
	v_mfma_f32_16x16x32_bf16 v[110:113], v[152:155], v[196:199], v[110:113]
	v_mfma_f32_16x16x32_bf16 v[106:109], v[164:167], v[196:199], v[106:109]
	v_mfma_f32_16x16x32_bf16 v[94:97], v[152:155], v[204:207], v[94:97]
	v_mfma_f32_16x16x32_bf16 v[90:93], v[164:167], v[204:207], v[90:93]
	v_mfma_f32_16x16x32_bf16 v[78:81], v[152:155], v[212:215], v[78:81]
	v_mfma_f32_16x16x32_bf16 v[74:77], v[164:167], v[212:215], v[74:77]
	s_setprio 0
	s_setprio 1
	v_mfma_f32_16x16x32_bf16 v[118:121], v[168:171], v[184:187], v[118:121]
	v_mfma_f32_16x16x32_bf16 v[114:117], v[176:179], v[184:187], v[114:117]
	v_mfma_f32_16x16x32_bf16 v[102:105], v[168:171], v[192:195], v[102:105]
	v_mfma_f32_16x16x32_bf16 v[98:101], v[176:179], v[192:195], v[98:101]
	v_mfma_f32_16x16x32_bf16 v[86:89], v[168:171], v[200:203], v[86:89]
	v_mfma_f32_16x16x32_bf16 v[82:85], v[176:179], v[200:203], v[82:85]
	v_mfma_f32_16x16x32_bf16 v[70:73], v[168:171], v[208:211], v[70:73]
	v_mfma_f32_16x16x32_bf16 v[66:69], v[176:179], v[208:211], v[66:69]
	v_mfma_f32_16x16x32_bf16 v[118:121], v[172:175], v[188:191], v[118:121]
	v_mfma_f32_16x16x32_bf16 v[114:117], v[180:183], v[188:191], v[114:117]
	v_mfma_f32_16x16x32_bf16 v[102:105], v[172:175], v[196:199], v[102:105]
	v_mfma_f32_16x16x32_bf16 v[98:101], v[180:183], v[196:199], v[98:101]
	v_mfma_f32_16x16x32_bf16 v[86:89], v[172:175], v[204:207], v[86:89]
	v_mfma_f32_16x16x32_bf16 v[82:85], v[180:183], v[204:207], v[82:85]
	v_mfma_f32_16x16x32_bf16 v[70:73], v[172:175], v[212:215], v[70:73]
	v_mfma_f32_16x16x32_bf16 v[66:69], v[180:183], v[212:215], v[66:69]
	s_barrier
	s_setprio 0
	s_add_i32 s56, s56, s39
	v_lshl_add_u64 v[226:227], s[54:55], 0, v[134:135]
	s_mov_b32 m0, s56
	ds_read_b128 v[184:187], v147 offset:16384
	ds_read_b128 v[188:191], v147 offset:17408
	ds_read_b128 v[192:195], v147 offset:18432
	ds_read_b128 v[196:199], v147 offset:19456
	ds_read_b128 v[200:203], v147 offset:20480
	ds_read_b128 v[204:207], v147 offset:21504
	ds_read_b128 v[208:211], v147 offset:22528
	ds_read_b128 v[212:215], v147 offset:23552
	global_load_lds_dwordx4 v[226:227], off
	s_add_i32 m0, s56, 0x2000
	v_lshl_add_u64 v[228:229], s[54:55], 0, v[130:131]
	s_add_u32 s54, s54, s37
	s_addc_u32 s55, s55, 0
	s_add_i32 s56, s57, s39
	global_load_lds_dwordx4 v[228:229], off
	v_lshl_add_u64 v[230:231], s[54:55], 0, v[134:135]
	s_mov_b32 m0, s56
	v_lshl_add_u64 v[242:243], s[54:55], 0, v[130:131]
	global_load_lds_dwordx4 v[230:231], off
	s_add_i32 m0, s56, 0x2000
	v_lshl_add_u64 v[244:245], s[8:9], 0, v[136:137]
	global_load_lds_dwordx4 v[242:243], off
	s_mov_b32 m0, s40
	v_lshl_add_u64 v[246:247], s[8:9], 0, v[132:133]
	global_load_lds_dwordx4 v[244:245], off
	s_mov_b32 m0, s41
	s_nop 0
	global_load_lds_dwordx4 v[246:247], off
	s_waitcnt vmcnt(8)
	s_waitcnt lgkmcnt(0)
	s_setprio 1
	s_barrier
	s_waitcnt lgkmcnt(0)
	v_mfma_f32_16x16x32_bf16 v[62:65], v[148:151], v[184:187], v[62:65]
	v_mfma_f32_16x16x32_bf16 v[58:61], v[156:159], v[184:187], v[58:61]
	v_mfma_f32_16x16x32_bf16 v[46:49], v[148:151], v[192:195], v[46:49]
	v_mfma_f32_16x16x32_bf16 v[42:45], v[156:159], v[192:195], v[42:45]
	v_mfma_f32_16x16x32_bf16 v[30:33], v[148:151], v[200:203], v[30:33]
	v_mfma_f32_16x16x32_bf16 v[26:29], v[156:159], v[200:203], v[26:29]
	v_mfma_f32_16x16x32_bf16 v[14:17], v[148:151], v[208:211], v[14:17]
	v_mfma_f32_16x16x32_bf16 v[10:13], v[156:159], v[208:211], v[10:13]
	v_mfma_f32_16x16x32_bf16 v[62:65], v[152:155], v[188:191], v[62:65]
	v_mfma_f32_16x16x32_bf16 v[58:61], v[164:167], v[188:191], v[58:61]
	v_mfma_f32_16x16x32_bf16 v[46:49], v[152:155], v[196:199], v[46:49]
	v_mfma_f32_16x16x32_bf16 v[42:45], v[164:167], v[196:199], v[42:45]
	v_mfma_f32_16x16x32_bf16 v[30:33], v[152:155], v[204:207], v[30:33]
	v_mfma_f32_16x16x32_bf16 v[26:29], v[164:167], v[204:207], v[26:29]
	v_mfma_f32_16x16x32_bf16 v[14:17], v[152:155], v[212:215], v[14:17]
	v_mfma_f32_16x16x32_bf16 v[10:13], v[164:167], v[212:215], v[10:13]
	s_setprio 0
	s_setprio 1
	v_mfma_f32_16x16x32_bf16 v[54:57], v[168:171], v[184:187], v[54:57]
	v_mfma_f32_16x16x32_bf16 v[50:53], v[176:179], v[184:187], v[50:53]
	v_mfma_f32_16x16x32_bf16 v[38:41], v[168:171], v[192:195], v[38:41]
	v_mfma_f32_16x16x32_bf16 v[34:37], v[176:179], v[192:195], v[34:37]
	v_mfma_f32_16x16x32_bf16 v[22:25], v[168:171], v[200:203], v[22:25]
	v_mfma_f32_16x16x32_bf16 v[18:21], v[176:179], v[200:203], v[18:21]
	v_mfma_f32_16x16x32_bf16 v[6:9], v[168:171], v[208:211], v[6:9]
	v_mfma_f32_16x16x32_bf16 v[2:5], v[176:179], v[208:211], v[2:5]
	v_mfma_f32_16x16x32_bf16 v[54:57], v[172:175], v[188:191], v[54:57]
	v_mfma_f32_16x16x32_bf16 v[50:53], v[180:183], v[188:191], v[50:53]
	v_mfma_f32_16x16x32_bf16 v[38:41], v[172:175], v[196:199], v[38:41]
	v_mfma_f32_16x16x32_bf16 v[34:37], v[180:183], v[196:199], v[34:37]
	v_mfma_f32_16x16x32_bf16 v[22:25], v[172:175], v[204:207], v[22:25]
	v_mfma_f32_16x16x32_bf16 v[18:21], v[180:183], v[204:207], v[18:21]
	v_mfma_f32_16x16x32_bf16 v[6:9], v[172:175], v[212:215], v[6:9]
	v_mfma_f32_16x16x32_bf16 v[2:5], v[180:183], v[212:215], v[2:5]
	s_barrier
	s_setprio 0
	s_add_i32 s54, 0, 0x18000
	v_add_u32_e32 v0, s54, v141
	s_add_i32 s55, 0, 0x1c000
	ds_read_b128 v[148:151], v0
	ds_read_b128 v[152:155], v0 offset:1024
	ds_read_b128 v[156:159], v0 offset:2048
	ds_read_b128 v[164:167], v0 offset:3072
	v_add_u32_e32 v0, s55, v141
	ds_read_b128 v[168:171], v0
	ds_read_b128 v[172:175], v0 offset:1024
	ds_read_b128 v[176:179], v0 offset:2048
	ds_read_b128 v[180:183], v0 offset:3072
	s_add_u32 s8, s8, 0x40000
	s_addc_u32 s9, s9, 0
	s_mov_b32 m0, s42
	v_lshl_add_u64 v[232:233], s[8:9], 0, v[136:137]
	ds_read_b128 v[184:187], v147 offset:32768
	ds_read_b128 v[188:191], v147 offset:33792
	ds_read_b128 v[192:195], v147 offset:34816
	ds_read_b128 v[196:199], v147 offset:35840
	ds_read_b128 v[200:203], v147 offset:36864
	ds_read_b128 v[204:207], v147 offset:37888
	ds_read_b128 v[208:211], v147 offset:38912
	ds_read_b128 v[212:215], v147 offset:39936
	global_load_lds_dwordx4 v[232:233], off
	v_lshl_add_u64 v[232:233], s[8:9], 0, v[132:133]
	s_mov_b32 m0, s43
	s_nop 0
	global_load_lds_dwordx4 v[232:233], off
	s_waitcnt vmcnt(8)
	s_waitcnt lgkmcnt(0)
	s_setprio 1
	s_barrier
	s_waitcnt lgkmcnt(0)
	v_mfma_f32_16x16x32_bf16 v[126:129], v[148:151], v[184:187], v[126:129]
	v_mfma_f32_16x16x32_bf16 v[122:125], v[156:159], v[184:187], v[122:125]
	v_mfma_f32_16x16x32_bf16 v[110:113], v[148:151], v[192:195], v[110:113]
	v_mfma_f32_16x16x32_bf16 v[106:109], v[156:159], v[192:195], v[106:109]
	v_mfma_f32_16x16x32_bf16 v[94:97], v[148:151], v[200:203], v[94:97]
	v_mfma_f32_16x16x32_bf16 v[90:93], v[156:159], v[200:203], v[90:93]
	v_mfma_f32_16x16x32_bf16 v[78:81], v[148:151], v[208:211], v[78:81]
	v_mfma_f32_16x16x32_bf16 v[74:77], v[156:159], v[208:211], v[74:77]
	v_mfma_f32_16x16x32_bf16 v[126:129], v[152:155], v[188:191], v[126:129]
	v_mfma_f32_16x16x32_bf16 v[122:125], v[164:167], v[188:191], v[122:125]
	v_mfma_f32_16x16x32_bf16 v[110:113], v[152:155], v[196:199], v[110:113]
	v_mfma_f32_16x16x32_bf16 v[106:109], v[164:167], v[196:199], v[106:109]
	v_mfma_f32_16x16x32_bf16 v[94:97], v[152:155], v[204:207], v[94:97]
	v_mfma_f32_16x16x32_bf16 v[90:93], v[164:167], v[204:207], v[90:93]
	v_mfma_f32_16x16x32_bf16 v[78:81], v[152:155], v[212:215], v[78:81]
	v_mfma_f32_16x16x32_bf16 v[74:77], v[164:167], v[212:215], v[74:77]
	s_setprio 0
	s_setprio 1
	v_mfma_f32_16x16x32_bf16 v[118:121], v[168:171], v[184:187], v[118:121]
	v_mfma_f32_16x16x32_bf16 v[114:117], v[176:179], v[184:187], v[114:117]
	v_mfma_f32_16x16x32_bf16 v[102:105], v[168:171], v[192:195], v[102:105]
	v_mfma_f32_16x16x32_bf16 v[98:101], v[176:179], v[192:195], v[98:101]
	v_mfma_f32_16x16x32_bf16 v[86:89], v[168:171], v[200:203], v[86:89]
	v_mfma_f32_16x16x32_bf16 v[82:85], v[176:179], v[200:203], v[82:85]
	v_mfma_f32_16x16x32_bf16 v[70:73], v[168:171], v[208:211], v[70:73]
	v_mfma_f32_16x16x32_bf16 v[66:69], v[176:179], v[208:211], v[66:69]
	v_mfma_f32_16x16x32_bf16 v[118:121], v[172:175], v[188:191], v[118:121]
	v_mfma_f32_16x16x32_bf16 v[114:117], v[180:183], v[188:191], v[114:117]
	v_mfma_f32_16x16x32_bf16 v[102:105], v[172:175], v[196:199], v[102:105]
	v_mfma_f32_16x16x32_bf16 v[98:101], v[180:183], v[196:199], v[98:101]
	v_mfma_f32_16x16x32_bf16 v[86:89], v[172:175], v[204:207], v[86:89]
	v_mfma_f32_16x16x32_bf16 v[82:85], v[180:183], v[204:207], v[82:85]
	v_mfma_f32_16x16x32_bf16 v[70:73], v[172:175], v[212:215], v[70:73]
	v_mfma_f32_16x16x32_bf16 v[66:69], v[180:183], v[212:215], v[66:69]
	s_barrier
	s_setprio 0
	s_add_i32 s8, s54, s39
	v_lshl_add_u64 v[226:227], v[226:227], 0, s[94:95]
	s_mov_b32 m0, s8
	ds_read_b128 v[184:187], v147 offset:49152
	ds_read_b128 v[188:191], v147 offset:50176
	ds_read_b128 v[192:195], v147 offset:51200
	ds_read_b128 v[196:199], v147 offset:52224
	ds_read_b128 v[200:203], v147 offset:53248
	ds_read_b128 v[204:207], v147 offset:54272
	ds_read_b128 v[208:211], v147 offset:55296
	ds_read_b128 v[212:215], v147 offset:56320
	global_load_lds_dwordx4 v[226:227], off
	v_lshl_add_u64 v[226:227], v[228:229], 0, s[94:95]
	s_add_i32 m0, s8, 0x2000
	s_add_i32 s8, s55, s39
	global_load_lds_dwordx4 v[226:227], off
	v_lshl_add_u64 v[226:227], v[230:231], 0, s[94:95]
	s_mov_b32 m0, s8
	s_nop 0
	global_load_lds_dwordx4 v[226:227], off
	v_lshl_add_u64 v[226:227], v[242:243], 0, s[94:95]
	s_add_i32 m0, s8, 0x2000
	s_nop 0
	global_load_lds_dwordx4 v[226:227], off
	v_lshl_add_u64 v[226:227], v[244:245], 0, s[94:95]
	s_mov_b32 m0, s44
	s_nop 0
	global_load_lds_dwordx4 v[226:227], off
	v_lshl_add_u64 v[226:227], v[246:247], 0, s[94:95]
	s_mov_b32 m0, s45
	s_nop 0
	global_load_lds_dwordx4 v[226:227], off
	s_waitcnt vmcnt(8)
	s_waitcnt lgkmcnt(0)
	s_setprio 1
	s_barrier
	s_waitcnt lgkmcnt(0)
	v_mfma_f32_16x16x32_bf16 v[62:65], v[148:151], v[184:187], v[62:65]
	v_mfma_f32_16x16x32_bf16 v[58:61], v[156:159], v[184:187], v[58:61]
	v_mfma_f32_16x16x32_bf16 v[46:49], v[148:151], v[192:195], v[46:49]
	v_mfma_f32_16x16x32_bf16 v[42:45], v[156:159], v[192:195], v[42:45]
	v_mfma_f32_16x16x32_bf16 v[30:33], v[148:151], v[200:203], v[30:33]
	v_mfma_f32_16x16x32_bf16 v[26:29], v[156:159], v[200:203], v[26:29]
	v_mfma_f32_16x16x32_bf16 v[14:17], v[148:151], v[208:211], v[14:17]
	v_mfma_f32_16x16x32_bf16 v[10:13], v[156:159], v[208:211], v[10:13]
	v_mfma_f32_16x16x32_bf16 v[62:65], v[152:155], v[188:191], v[62:65]
	v_mfma_f32_16x16x32_bf16 v[58:61], v[164:167], v[188:191], v[58:61]
	v_mfma_f32_16x16x32_bf16 v[46:49], v[152:155], v[196:199], v[46:49]
	v_mfma_f32_16x16x32_bf16 v[42:45], v[164:167], v[196:199], v[42:45]
	v_mfma_f32_16x16x32_bf16 v[30:33], v[152:155], v[204:207], v[30:33]
	v_mfma_f32_16x16x32_bf16 v[26:29], v[164:167], v[204:207], v[26:29]
	v_mfma_f32_16x16x32_bf16 v[14:17], v[152:155], v[212:215], v[14:17]
	v_mfma_f32_16x16x32_bf16 v[10:13], v[164:167], v[212:215], v[10:13]
	s_setprio 0
	s_setprio 1
	v_mfma_f32_16x16x32_bf16 v[54:57], v[168:171], v[184:187], v[54:57]
	v_mfma_f32_16x16x32_bf16 v[50:53], v[176:179], v[184:187], v[50:53]
	v_mfma_f32_16x16x32_bf16 v[38:41], v[168:171], v[192:195], v[38:41]
	v_mfma_f32_16x16x32_bf16 v[34:37], v[176:179], v[192:195], v[34:37]
	v_mfma_f32_16x16x32_bf16 v[22:25], v[168:171], v[200:203], v[22:25]
	v_mfma_f32_16x16x32_bf16 v[18:21], v[176:179], v[200:203], v[18:21]
	v_mfma_f32_16x16x32_bf16 v[6:9], v[168:171], v[208:211], v[6:9]
	v_mfma_f32_16x16x32_bf16 v[2:5], v[176:179], v[208:211], v[2:5]
	v_mfma_f32_16x16x32_bf16 v[54:57], v[172:175], v[188:191], v[54:57]
	v_mfma_f32_16x16x32_bf16 v[50:53], v[180:183], v[188:191], v[50:53]
	v_mfma_f32_16x16x32_bf16 v[38:41], v[172:175], v[196:199], v[38:41]
	v_mfma_f32_16x16x32_bf16 v[34:37], v[180:183], v[196:199], v[34:37]
	v_mfma_f32_16x16x32_bf16 v[22:25], v[172:175], v[204:207], v[22:25]
	v_mfma_f32_16x16x32_bf16 v[18:21], v[180:183], v[204:207], v[18:21]
	v_mfma_f32_16x16x32_bf16 v[6:9], v[172:175], v[212:215], v[6:9]
	v_mfma_f32_16x16x32_bf16 v[2:5], v[180:183], v[212:215], v[2:5]
	s_barrier
	s_setprio 0
	s_add_u32 s0, s0, 0x100
	s_addc_u32 s1, s1, 0
	s_add_u32 s34, s34, 0x100
	s_addc_u32 s35, s35, 0
	s_cmp_ge_u32 s53, s5
	s_mov_b32 s8, s53
	s_cbranch_scc0 .LBB0_402
	s_and_b64 vcc, exec, s[20:21]
	s_cbranch_vccz .LBB0_405
	s_barrier
